# v31: accumulator zeroing between GEMM units uses 64-bit moves (v_mov_b64) in 6 of the GEMM bodies, on top of v30
# speedup vs baseline: 1.0025x; 1.0025x over previous
; template <class Epi, class Sched, bool ALIGN_EPI = false, bool SP2 = false>
; __device__ __forceinline__ void gemm_phase(PG8_LAS unsigned char* lds, const Gemm g, const Sched& S, const Epi& E) {
;     ...
;         const char* nA = has_next ? (const char*)g.A + (size_t)nxt.pm * tstep : cA; const char* nB = has_next ? (const char*)g.Bt + (size_t)nxt.pn * tstep : cB;
;         const char* nA2 = (has_next && g.nt2) ? (const char*)g.A2 + (size_t)nxt.pm * tstep - (size_t)ns * (BK * 2) : cA2; const char* nB2 = (has_next && g.nt2) ? (const char*)g.Bt2 + (size_t)nxt.pn * tstep - (size_t)ns * (BK * 2) : cB2;
;     ...
; #pragma unroll
;         for (int a = 0; a < 2; ++a)
; #pragma unroll
;             for (int b = 0; b < 2; ++b)
; #pragma unroll
;                 for (int m = 0; m < 4; ++m)
; #pragma unroll
;                     for (int n = 0; n < 2; ++n) acc[a][b][m][n] = (f32x4){0.f, 0.f, 0.f, 0.f};
.LBB0_93:
	s_ashr_i32 s73, s72, 31
	s_lshl_b64 s[26:27], s[72:73], 20
	s_add_u32 s74, s30, s26
	s_addc_u32 s75, s31, s27
	s_and_b64 s[26:27], s[4:5], exec
	s_cselect_b32 s7, s75, s79
	s_cselect_b32 s26, s74, s78
	s_ashr_i32 s71, s70, 31
	s_lshl_b64 s[34:35], s[70:71], 20
	v_readlane_b32 s24, v255, 0
	v_readlane_b32 s25, v255, 1
	s_add_u32 s76, s24, s34
	s_addc_u32 s77, s25, s35
	s_and_b64 s[34:35], s[4:5], exec
	v_mov_b32_e32 v2, 0
	s_cselect_b32 s27, s77, s9
	s_cselect_b32 s57, s76, s8
	s_mov_b32 s73, -2
	s_mov_b64 s[80:81], 0x80080
	s_waitcnt lgkmcnt(0)
	v_mov_b32_e32 v3, v2
	v_mov_b64_e32 v[4:5], v[2:3]
	v_mov_b64_e32 v[6:7], v[2:3]
	v_mov_b64_e32 v[8:9], v[2:3]
	v_mov_b64_e32 v[10:11], v[2:3]
	v_mov_b64_e32 v[12:13], v[2:3]
	v_mov_b64_e32 v[14:15], v[2:3]
	v_mov_b64_e32 v[16:17], v[2:3]
	v_mov_b64_e32 v[18:19], v[2:3]
	v_mov_b64_e32 v[20:21], v[2:3]
	v_mov_b64_e32 v[22:23], v[2:3]
	v_mov_b64_e32 v[24:25], v[2:3]
	v_mov_b64_e32 v[26:27], v[2:3]
	v_mov_b64_e32 v[28:29], v[2:3]
	v_mov_b64_e32 v[30:31], v[2:3]
	v_mov_b64_e32 v[32:33], v[2:3]
	v_mov_b64_e32 v[34:35], v[2:3]
	v_mov_b64_e32 v[36:37], v[2:3]
	v_mov_b64_e32 v[38:39], v[2:3]
	v_mov_b64_e32 v[40:41], v[2:3]
	v_mov_b64_e32 v[42:43], v[2:3]
	v_mov_b64_e32 v[44:45], v[2:3]
	v_mov_b64_e32 v[46:47], v[2:3]
	v_mov_b64_e32 v[48:49], v[2:3]
	v_mov_b64_e32 v[50:51], v[2:3]
	v_mov_b64_e32 v[52:53], v[2:3]
	v_mov_b64_e32 v[54:55], v[2:3]
	v_mov_b64_e32 v[56:57], v[2:3]
	v_mov_b64_e32 v[58:59], v[2:3]
	v_mov_b64_e32 v[60:61], v[2:3]
	v_mov_b64_e32 v[62:63], v[2:3]
	v_mov_b64_e32 v[64:65], v[2:3]
	v_mov_b64_e32 v[66:67], v[2:3]
	v_mov_b64_e32 v[68:69], v[2:3]
	v_mov_b64_e32 v[70:71], v[2:3]
	v_mov_b64_e32 v[72:73], v[2:3]
	v_mov_b64_e32 v[74:75], v[2:3]
	v_mov_b64_e32 v[76:77], v[2:3]
	v_mov_b64_e32 v[78:79], v[2:3]
	v_mov_b64_e32 v[80:81], v[2:3]
	v_mov_b64_e32 v[82:83], v[2:3]
	v_mov_b64_e32 v[84:85], v[2:3]
	v_mov_b64_e32 v[86:87], v[2:3]
	v_mov_b64_e32 v[88:89], v[2:3]
	v_mov_b64_e32 v[90:91], v[2:3]
	v_mov_b64_e32 v[92:93], v[2:3]
	v_mov_b64_e32 v[94:95], v[2:3]
	v_mov_b64_e32 v[96:97], v[2:3]
	v_mov_b64_e32 v[98:99], v[2:3]
	v_mov_b64_e32 v[100:101], v[2:3]
	v_mov_b64_e32 v[102:103], v[2:3]
	v_mov_b64_e32 v[104:105], v[2:3]
	v_mov_b64_e32 v[106:107], v[2:3]
	v_mov_b64_e32 v[108:109], v[2:3]
	v_mov_b64_e32 v[110:111], v[2:3]
	v_mov_b64_e32 v[112:113], v[2:3]
	v_mov_b64_e32 v[114:115], v[2:3]
	v_mov_b64_e32 v[116:117], v[2:3]
	v_mov_b64_e32 v[118:119], v[2:3]
	v_mov_b64_e32 v[120:121], v[2:3]
	v_mov_b64_e32 v[122:123], v[2:3]
	v_mov_b64_e32 v[124:125], v[2:3]
	v_mov_b64_e32 v[126:127], v[2:3]
	v_mov_b64_e32 v[128:129], v[2:3]
	v_lshl_add_u64 v[130:131], s[78:79], 0, v[162:163]
	v_lshl_add_u64 v[132:133], s[78:79], 0, v[164:165]

; template <class Epi, class Sched, bool ALIGN_EPI = false, bool SP2 = false>
; __device__ __forceinline__ void gemm_phase(PG8_LAS unsigned char* lds, const Gemm g, const Sched& S, const Epi& E) {
;     ...
;         const char* nA = has_next ? (const char*)g.A + (size_t)nxt.pm * tstep : cA; const char* nB = has_next ? (const char*)g.Bt + (size_t)nxt.pn * tstep : cB;
;         const char* nA2 = (has_next && g.nt2) ? (const char*)g.A2 + (size_t)nxt.pm * tstep - (size_t)ns * (BK * 2) : cA2; const char* nB2 = (has_next && g.nt2) ? (const char*)g.Bt2 + (size_t)nxt.pn * tstep - (size_t)ns * (BK * 2) : cB2;
;     ...
; #pragma unroll
;         for (int a = 0; a < 2; ++a)
; #pragma unroll
;             for (int b = 0; b < 2; ++b)
; #pragma unroll
;                 for (int m = 0; m < 4; ++m)
; #pragma unroll
;                     for (int n = 0; n < 2; ++n) acc[a][b][m][n] = (f32x4){0.f, 0.f, 0.f, 0.f};
.LBB0_294:
	s_ashr_i32 s61, s60, 31
	s_lshl_b64 s[34:35], s[60:61], 20
	s_add_u32 s62, s26, s34
	s_addc_u32 s63, s27, s35
	s_and_b64 s[34:35], s[2:3], exec
	s_cselect_b32 s61, s63, s71
	s_cselect_b32 s90, s62, s70
	s_ashr_i32 s59, s58, 31
	s_lshl_b64 s[34:35], s[58:59], 20
	s_add_u32 s64, s30, s34
	s_addc_u32 s65, s31, s35
	s_and_b64 s[34:35], s[2:3], exec
	v_mov_b32_e32 v2, 0
	s_cselect_b32 s59, s65, s69
	s_cselect_b32 s91, s64, s68
	v_lshl_add_u64 v[146:147], s[70:71], 0, v[138:139]
	v_lshl_add_u64 v[148:149], s[70:71], 0, v[140:141]
	s_mov_b32 s74, -2
	s_mov_b64 s[72:73], 0x80080
	v_mov_b32_e32 v3, v2
	v_mov_b64_e32 v[4:5], v[2:3]
	v_mov_b64_e32 v[6:7], v[2:3]
	v_mov_b64_e32 v[8:9], v[2:3]
	v_mov_b64_e32 v[10:11], v[2:3]
	v_mov_b64_e32 v[12:13], v[2:3]
	v_mov_b64_e32 v[14:15], v[2:3]
	v_mov_b64_e32 v[16:17], v[2:3]
	v_mov_b64_e32 v[18:19], v[2:3]
	v_mov_b64_e32 v[20:21], v[2:3]
	v_mov_b64_e32 v[22:23], v[2:3]
	v_mov_b64_e32 v[24:25], v[2:3]
	v_mov_b64_e32 v[26:27], v[2:3]
	v_mov_b64_e32 v[28:29], v[2:3]
	v_mov_b64_e32 v[30:31], v[2:3]
	v_mov_b64_e32 v[32:33], v[2:3]
	v_mov_b64_e32 v[34:35], v[2:3]
	v_mov_b64_e32 v[36:37], v[2:3]
	v_mov_b64_e32 v[38:39], v[2:3]
	v_mov_b64_e32 v[40:41], v[2:3]
	v_mov_b64_e32 v[42:43], v[2:3]
	v_mov_b64_e32 v[44:45], v[2:3]
	v_mov_b64_e32 v[46:47], v[2:3]
	v_mov_b64_e32 v[48:49], v[2:3]
	v_mov_b64_e32 v[50:51], v[2:3]
	v_mov_b64_e32 v[52:53], v[2:3]
	v_mov_b64_e32 v[54:55], v[2:3]
	v_mov_b64_e32 v[56:57], v[2:3]
	v_mov_b64_e32 v[58:59], v[2:3]
	v_mov_b64_e32 v[60:61], v[2:3]
	v_mov_b64_e32 v[62:63], v[2:3]
	v_mov_b64_e32 v[64:65], v[2:3]
	v_mov_b64_e32 v[66:67], v[2:3]
	v_mov_b64_e32 v[68:69], v[2:3]
	v_mov_b64_e32 v[70:71], v[2:3]
	v_mov_b64_e32 v[72:73], v[2:3]
	v_mov_b64_e32 v[74:75], v[2:3]
	v_mov_b64_e32 v[76:77], v[2:3]
	v_mov_b64_e32 v[78:79], v[2:3]
	v_mov_b64_e32 v[80:81], v[2:3]
	v_mov_b64_e32 v[82:83], v[2:3]
	v_mov_b64_e32 v[84:85], v[2:3]
	v_mov_b64_e32 v[86:87], v[2:3]
	v_mov_b64_e32 v[88:89], v[2:3]
	v_mov_b64_e32 v[90:91], v[2:3]
	v_mov_b64_e32 v[92:93], v[2:3]
	v_mov_b64_e32 v[94:95], v[2:3]
	v_mov_b64_e32 v[96:97], v[2:3]
	v_mov_b64_e32 v[98:99], v[2:3]
	v_mov_b64_e32 v[100:101], v[2:3]
	v_mov_b64_e32 v[102:103], v[2:3]
	v_mov_b64_e32 v[104:105], v[2:3]
	v_mov_b64_e32 v[106:107], v[2:3]
	v_mov_b64_e32 v[108:109], v[2:3]
	v_mov_b64_e32 v[110:111], v[2:3]
	v_mov_b64_e32 v[112:113], v[2:3]
	v_mov_b64_e32 v[114:115], v[2:3]
	v_mov_b64_e32 v[116:117], v[2:3]
	v_mov_b64_e32 v[118:119], v[2:3]
	v_mov_b64_e32 v[120:121], v[2:3]
	v_mov_b64_e32 v[122:123], v[2:3]
	v_mov_b64_e32 v[124:125], v[2:3]
	v_mov_b64_e32 v[126:127], v[2:3]
	v_mov_b64_e32 v[128:129], v[2:3]

; template <class Epi, class Sched, bool ALIGN_EPI = false, bool SP2 = false>
; __device__ __forceinline__ void gemm_phase(PG8_LAS unsigned char* lds, const Gemm g, const Sched& S, const Epi& E) {
;     ...
;         const char* nA = has_next ? (const char*)g.A + (size_t)nxt.pm * tstep : cA; const char* nB = has_next ? (const char*)g.Bt + (size_t)nxt.pn * tstep : cB;
;         const char* nA2 = (has_next && g.nt2) ? (const char*)g.A2 + (size_t)nxt.pm * tstep - (size_t)ns * (BK * 2) : cA2; const char* nB2 = (has_next && g.nt2) ? (const char*)g.Bt2 + (size_t)nxt.pn * tstep - (size_t)ns * (BK * 2) : cB2;
;     ...
; #pragma unroll
;         for (int a = 0; a < 2; ++a)
; #pragma unroll
;             for (int b = 0; b < 2; ++b)
; #pragma unroll
;                 for (int m = 0; m < 4; ++m)
; #pragma unroll
;                     for (int n = 0; n < 2; ++n) acc[a][b][m][n] = (f32x4){0.f, 0.f, 0.f, 0.f};
.LBB0_733:
	s_ashr_i32 s63, s62, 31
	s_lshl_b64 s[34:35], s[62:63], 20
	s_add_u32 s64, s48, s34
	s_addc_u32 s65, s49, s35
	s_and_b64 s[34:35], s[2:3], exec
	s_cselect_b32 s63, s65, s71
	s_cselect_b32 s86, s64, s70
	s_ashr_i32 s61, s60, 31
	s_lshl_b64 s[34:35], s[60:61], 20
	v_readlane_b32 s24, v255, 4
	v_readlane_b32 s25, v255, 5
	s_add_u32 s66, s24, s34
	s_addc_u32 s67, s25, s35
	s_and_b64 s[34:35], s[2:3], exec
	v_mov_b32_e32 v2, 0
	s_cselect_b32 s61, s67, s69
	s_cselect_b32 s87, s66, s68
	v_lshl_add_u64 v[146:147], s[70:71], 0, v[138:139]
	v_lshl_add_u64 v[148:149], s[70:71], 0, v[140:141]
	s_mov_b32 s74, -2
	s_mov_b64 s[72:73], 0x80080
	v_mov_b32_e32 v3, v2
	v_mov_b64_e32 v[4:5], v[2:3]
	v_mov_b64_e32 v[6:7], v[2:3]
	v_mov_b64_e32 v[8:9], v[2:3]
	v_mov_b64_e32 v[10:11], v[2:3]
	v_mov_b64_e32 v[12:13], v[2:3]
	v_mov_b64_e32 v[14:15], v[2:3]
	v_mov_b64_e32 v[16:17], v[2:3]
	v_mov_b64_e32 v[18:19], v[2:3]
	v_mov_b64_e32 v[20:21], v[2:3]
	v_mov_b64_e32 v[22:23], v[2:3]
	v_mov_b64_e32 v[24:25], v[2:3]
	v_mov_b64_e32 v[26:27], v[2:3]
	v_mov_b64_e32 v[28:29], v[2:3]
	v_mov_b64_e32 v[30:31], v[2:3]
	v_mov_b64_e32 v[32:33], v[2:3]
	v_mov_b64_e32 v[34:35], v[2:3]
	v_mov_b64_e32 v[36:37], v[2:3]
	v_mov_b64_e32 v[38:39], v[2:3]
	v_mov_b64_e32 v[40:41], v[2:3]
	v_mov_b64_e32 v[42:43], v[2:3]
	v_mov_b64_e32 v[44:45], v[2:3]
	v_mov_b64_e32 v[46:47], v[2:3]
	v_mov_b64_e32 v[48:49], v[2:3]
	v_mov_b64_e32 v[50:51], v[2:3]
	v_mov_b64_e32 v[52:53], v[2:3]
	v_mov_b64_e32 v[54:55], v[2:3]
	v_mov_b64_e32 v[56:57], v[2:3]
	v_mov_b64_e32 v[58:59], v[2:3]
	v_mov_b64_e32 v[60:61], v[2:3]
	v_mov_b64_e32 v[62:63], v[2:3]
	v_mov_b64_e32 v[64:65], v[2:3]
	v_mov_b64_e32 v[66:67], v[2:3]
	v_mov_b64_e32 v[68:69], v[2:3]
	v_mov_b64_e32 v[70:71], v[2:3]
	v_mov_b64_e32 v[72:73], v[2:3]
	v_mov_b64_e32 v[74:75], v[2:3]
	v_mov_b64_e32 v[76:77], v[2:3]
	v_mov_b64_e32 v[78:79], v[2:3]
	v_mov_b64_e32 v[80:81], v[2:3]
	v_mov_b64_e32 v[82:83], v[2:3]
	v_mov_b64_e32 v[84:85], v[2:3]
	v_mov_b64_e32 v[86:87], v[2:3]
	v_mov_b64_e32 v[88:89], v[2:3]
	v_mov_b64_e32 v[90:91], v[2:3]
	v_mov_b64_e32 v[92:93], v[2:3]
	v_mov_b64_e32 v[94:95], v[2:3]
	v_mov_b64_e32 v[96:97], v[2:3]
	v_mov_b64_e32 v[98:99], v[2:3]
	v_mov_b64_e32 v[100:101], v[2:3]
	v_mov_b64_e32 v[102:103], v[2:3]
	v_mov_b64_e32 v[104:105], v[2:3]
	v_mov_b64_e32 v[106:107], v[2:3]
	v_mov_b64_e32 v[108:109], v[2:3]
	v_mov_b64_e32 v[110:111], v[2:3]
	v_mov_b64_e32 v[112:113], v[2:3]
	v_mov_b64_e32 v[114:115], v[2:3]
	v_mov_b64_e32 v[116:117], v[2:3]
	v_mov_b64_e32 v[118:119], v[2:3]
	v_mov_b64_e32 v[120:121], v[2:3]
	v_mov_b64_e32 v[122:123], v[2:3]
	v_mov_b64_e32 v[124:125], v[2:3]
	v_mov_b64_e32 v[126:127], v[2:3]
	v_mov_b64_e32 v[128:129], v[2:3]

; template <class Epi, class Sched, bool ALIGN_EPI = false, bool SP2 = false>
; __device__ __forceinline__ void gemm_phase(PG8_LAS unsigned char* lds, const Gemm g, const Sched& S, const Epi& E) {
;     ...
;         const char* nA = has_next ? (const char*)g.A + (size_t)nxt.pm * tstep : cA; const char* nB = has_next ? (const char*)g.Bt + (size_t)nxt.pn * tstep : cB;
;         const char* nA2 = (has_next && g.nt2) ? (const char*)g.A2 + (size_t)nxt.pm * tstep - (size_t)ns * (BK * 2) : cA2; const char* nB2 = (has_next && g.nt2) ? (const char*)g.Bt2 + (size_t)nxt.pn * tstep - (size_t)ns * (BK * 2) : cB2;
;     ...
; #pragma unroll
;         for (int a = 0; a < 2; ++a)
; #pragma unroll
;             for (int b = 0; b < 2; ++b)
; #pragma unroll
;                 for (int m = 0; m < 4; ++m)
; #pragma unroll
;                     for (int n = 0; n < 2; ++n) acc[a][b][m][n] = (f32x4){0.f, 0.f, 0.f, 0.f};
.LBB0_749:
	s_ashr_i32 s55, s54, 31
	s_lshl_b64 s[34:35], s[54:55], 20
	s_add_u32 s58, s9, s34
	s_addc_u32 s59, s11, s35
	s_and_b64 s[34:35], s[56:57], exec
	s_cselect_b32 s55, s59, s67
	s_cselect_b32 s87, s58, s66
	s_ashr_i32 s53, s52, 31
	s_lshl_b64 s[34:35], s[52:53], 20
	v_readlane_b32 s24, v255, 6
	v_readlane_b32 s25, v255, 7
	s_add_u32 s60, s24, s34
	s_addc_u32 s61, s25, s35
	s_and_b64 s[34:35], s[56:57], exec
	v_mov_b32_e32 v2, 0
	s_cselect_b32 s53, s61, s65
	s_cselect_b32 s90, s60, s64
	v_lshl_add_u64 v[142:143], s[66:67], 0, v[138:139]
	v_lshl_add_u64 v[144:145], s[66:67], 0, v[140:141]
	s_mov_b32 s70, -2
	s_mov_b64 s[68:69], 0x80080
	v_mov_b32_e32 v3, v2
	v_mov_b64_e32 v[4:5], v[2:3]
	v_mov_b64_e32 v[6:7], v[2:3]
	v_mov_b64_e32 v[8:9], v[2:3]
	v_mov_b64_e32 v[10:11], v[2:3]
	v_mov_b64_e32 v[12:13], v[2:3]
	v_mov_b64_e32 v[14:15], v[2:3]
	v_mov_b64_e32 v[16:17], v[2:3]
	v_mov_b64_e32 v[18:19], v[2:3]
	v_mov_b64_e32 v[20:21], v[2:3]
	v_mov_b64_e32 v[22:23], v[2:3]
	v_mov_b64_e32 v[24:25], v[2:3]
	v_mov_b64_e32 v[26:27], v[2:3]
	v_mov_b64_e32 v[28:29], v[2:3]
	v_mov_b64_e32 v[30:31], v[2:3]
	v_mov_b64_e32 v[32:33], v[2:3]
	v_mov_b64_e32 v[34:35], v[2:3]
	v_mov_b64_e32 v[36:37], v[2:3]
	v_mov_b64_e32 v[38:39], v[2:3]
	v_mov_b64_e32 v[40:41], v[2:3]
	v_mov_b64_e32 v[42:43], v[2:3]
	v_mov_b64_e32 v[44:45], v[2:3]
	v_mov_b64_e32 v[46:47], v[2:3]
	v_mov_b64_e32 v[48:49], v[2:3]
	v_mov_b64_e32 v[50:51], v[2:3]
	v_mov_b64_e32 v[52:53], v[2:3]
	v_mov_b64_e32 v[54:55], v[2:3]
	v_mov_b64_e32 v[56:57], v[2:3]
	v_mov_b64_e32 v[58:59], v[2:3]
	v_mov_b64_e32 v[60:61], v[2:3]
	v_mov_b64_e32 v[62:63], v[2:3]
	v_mov_b64_e32 v[64:65], v[2:3]
	v_mov_b64_e32 v[66:67], v[2:3]
	v_mov_b64_e32 v[68:69], v[2:3]
	v_mov_b64_e32 v[70:71], v[2:3]
	v_mov_b64_e32 v[72:73], v[2:3]
	v_mov_b64_e32 v[74:75], v[2:3]
	v_mov_b64_e32 v[76:77], v[2:3]
	v_mov_b64_e32 v[78:79], v[2:3]
	v_mov_b64_e32 v[80:81], v[2:3]
	v_mov_b64_e32 v[82:83], v[2:3]
	v_mov_b64_e32 v[84:85], v[2:3]
	v_mov_b64_e32 v[86:87], v[2:3]
	v_mov_b64_e32 v[88:89], v[2:3]
	v_mov_b64_e32 v[90:91], v[2:3]
	v_mov_b64_e32 v[92:93], v[2:3]
	v_mov_b64_e32 v[94:95], v[2:3]
	v_mov_b64_e32 v[96:97], v[2:3]
	v_mov_b64_e32 v[98:99], v[2:3]
	v_mov_b64_e32 v[100:101], v[2:3]
	v_mov_b64_e32 v[102:103], v[2:3]
	v_mov_b64_e32 v[104:105], v[2:3]
	v_mov_b64_e32 v[106:107], v[2:3]
	v_mov_b64_e32 v[108:109], v[2:3]
	v_mov_b64_e32 v[110:111], v[2:3]
	v_mov_b64_e32 v[112:113], v[2:3]
	v_mov_b64_e32 v[114:115], v[2:3]
	v_mov_b64_e32 v[116:117], v[2:3]
	v_mov_b64_e32 v[118:119], v[2:3]
	v_mov_b64_e32 v[120:121], v[2:3]
	v_mov_b64_e32 v[122:123], v[2:3]
	v_mov_b64_e32 v[124:125], v[2:3]
	v_mov_b64_e32 v[126:127], v[2:3]
	v_mov_b64_e32 v[128:129], v[2:3]

; template <class Epi, class Sched, bool ALIGN_EPI = false, bool SP2 = false>
; __device__ __forceinline__ void gemm_phase(PG8_LAS unsigned char* lds, const Gemm g, const Sched& S, const Epi& E) {
;     ...
;         const char* nA = has_next ? (const char*)g.A + (size_t)nxt.pm * tstep : cA; const char* nB = has_next ? (const char*)g.Bt + (size_t)nxt.pn * tstep : cB;
;         const char* nA2 = (has_next && g.nt2) ? (const char*)g.A2 + (size_t)nxt.pm * tstep - (size_t)ns * (BK * 2) : cA2; const char* nB2 = (has_next && g.nt2) ? (const char*)g.Bt2 + (size_t)nxt.pn * tstep - (size_t)ns * (BK * 2) : cB2;
;     ...
; #pragma unroll
;         for (int a = 0; a < 2; ++a)
; #pragma unroll
;             for (int b = 0; b < 2; ++b)
; #pragma unroll
;                 for (int m = 0; m < 4; ++m)
; #pragma unroll
;                     for (int n = 0; n < 2; ++n) acc[a][b][m][n] = (f32x4){0.f, 0.f, 0.f, 0.f};
.LBB0_765:
	s_ashr_i32 s55, s54, 31
	s_lshl_b64 s[58:59], s[54:55], 20
	s_add_u32 s58, s26, s58
	s_addc_u32 s59, s27, s59
	s_and_b64 s[60:61], s[56:57], exec
	s_cselect_b32 s55, s59, s67
	s_cselect_b32 s87, s58, s66
	s_ashr_i32 s53, s52, 31
	s_lshl_b64 s[60:61], s[52:53], 20
	s_add_u32 s60, s9, s60
	s_addc_u32 s61, s11, s61
	s_and_b64 s[68:69], s[56:57], exec
	v_mov_b32_e32 v2, 0
	s_cselect_b32 s53, s61, s65
	s_cselect_b32 s90, s60, s64
	v_lshl_add_u64 v[142:143], s[66:67], 0, v[138:139]
	v_lshl_add_u64 v[144:145], s[66:67], 0, v[140:141]
	s_mov_b32 s70, -2
	s_mov_b64 s[68:69], 0x80080
	v_mov_b32_e32 v3, v2
	v_mov_b64_e32 v[4:5], v[2:3]
	v_mov_b64_e32 v[6:7], v[2:3]
	v_mov_b64_e32 v[8:9], v[2:3]
	v_mov_b64_e32 v[10:11], v[2:3]
	v_mov_b64_e32 v[12:13], v[2:3]
	v_mov_b64_e32 v[14:15], v[2:3]
	v_mov_b64_e32 v[16:17], v[2:3]
	v_mov_b64_e32 v[18:19], v[2:3]
	v_mov_b64_e32 v[20:21], v[2:3]
	v_mov_b64_e32 v[22:23], v[2:3]
	v_mov_b64_e32 v[24:25], v[2:3]
	v_mov_b64_e32 v[26:27], v[2:3]
	v_mov_b64_e32 v[28:29], v[2:3]
	v_mov_b64_e32 v[30:31], v[2:3]
	v_mov_b64_e32 v[32:33], v[2:3]
	v_mov_b64_e32 v[34:35], v[2:3]
	v_mov_b64_e32 v[36:37], v[2:3]
	v_mov_b64_e32 v[38:39], v[2:3]
	v_mov_b64_e32 v[40:41], v[2:3]
	v_mov_b64_e32 v[42:43], v[2:3]
	v_mov_b64_e32 v[44:45], v[2:3]
	v_mov_b64_e32 v[46:47], v[2:3]
	v_mov_b64_e32 v[48:49], v[2:3]
	v_mov_b64_e32 v[50:51], v[2:3]
	v_mov_b64_e32 v[52:53], v[2:3]
	v_mov_b64_e32 v[54:55], v[2:3]
	v_mov_b64_e32 v[56:57], v[2:3]
	v_mov_b64_e32 v[58:59], v[2:3]
	v_mov_b64_e32 v[60:61], v[2:3]
	v_mov_b64_e32 v[62:63], v[2:3]
	v_mov_b64_e32 v[64:65], v[2:3]
	v_mov_b64_e32 v[66:67], v[2:3]
	v_mov_b64_e32 v[68:69], v[2:3]
	v_mov_b64_e32 v[70:71], v[2:3]
	v_mov_b64_e32 v[72:73], v[2:3]
	v_mov_b64_e32 v[74:75], v[2:3]
	v_mov_b64_e32 v[76:77], v[2:3]
	v_mov_b64_e32 v[78:79], v[2:3]
	v_mov_b64_e32 v[80:81], v[2:3]
	v_mov_b64_e32 v[82:83], v[2:3]
	v_mov_b64_e32 v[84:85], v[2:3]
	v_mov_b64_e32 v[86:87], v[2:3]
	v_mov_b64_e32 v[88:89], v[2:3]
	v_mov_b64_e32 v[90:91], v[2:3]
	v_mov_b64_e32 v[92:93], v[2:3]
	v_mov_b64_e32 v[94:95], v[2:3]
	v_mov_b64_e32 v[96:97], v[2:3]
	v_mov_b64_e32 v[98:99], v[2:3]
	v_mov_b64_e32 v[100:101], v[2:3]
	v_mov_b64_e32 v[102:103], v[2:3]
	v_mov_b64_e32 v[104:105], v[2:3]
	v_mov_b64_e32 v[106:107], v[2:3]
	v_mov_b64_e32 v[108:109], v[2:3]
	v_mov_b64_e32 v[110:111], v[2:3]
	v_mov_b64_e32 v[112:113], v[2:3]
	v_mov_b64_e32 v[114:115], v[2:3]
	v_mov_b64_e32 v[116:117], v[2:3]
	v_mov_b64_e32 v[118:119], v[2:3]
	v_mov_b64_e32 v[120:121], v[2:3]
	v_mov_b64_e32 v[122:123], v[2:3]
	v_mov_b64_e32 v[124:125], v[2:3]
	v_mov_b64_e32 v[126:127], v[2:3]
	v_mov_b64_e32 v[128:129], v[2:3]

; template <class Epi, class Sched, bool ALIGN_EPI = false, bool SP2 = false>
; __device__ __forceinline__ void gemm_phase(PG8_LAS unsigned char* lds, const Gemm g, const Sched& S, const Epi& E) {
;     ...
; #pragma unroll
;         for (int a = 0; a < 2; ++a)
; #pragma unroll
;             for (int b = 0; b < 2; ++b)
; #pragma unroll
;                 for (int m = 0; m < 4; ++m)
; #pragma unroll
;                     for (int n = 0; n < 2; ++n) acc[a][b][m][n] = (f32x4){0.f, 0.f, 0.f, 0.f};
.LBB0_1089:
	v_mov_b32_e32 v2, 0
	v_lshl_add_u64 v[142:143], s[50:51], 0, v[134:135]
	v_lshl_add_u64 v[144:145], s[50:51], 0, v[136:137]
	s_mov_b32 s54, -2
	s_mov_b64 s[52:53], 0x160080
	v_mov_b32_e32 v3, v2
	v_mov_b64_e32 v[4:5], v[2:3]
	v_mov_b64_e32 v[6:7], v[2:3]
	v_mov_b64_e32 v[8:9], v[2:3]
	v_mov_b64_e32 v[10:11], v[2:3]
	v_mov_b64_e32 v[12:13], v[2:3]
	v_mov_b64_e32 v[14:15], v[2:3]
	v_mov_b64_e32 v[16:17], v[2:3]
	v_mov_b64_e32 v[18:19], v[2:3]
	v_mov_b64_e32 v[20:21], v[2:3]
	v_mov_b64_e32 v[22:23], v[2:3]
	v_mov_b64_e32 v[24:25], v[2:3]
	v_mov_b64_e32 v[26:27], v[2:3]
	v_mov_b64_e32 v[28:29], v[2:3]
	v_mov_b64_e32 v[30:31], v[2:3]
	v_mov_b64_e32 v[32:33], v[2:3]
	v_mov_b64_e32 v[34:35], v[2:3]
	v_mov_b64_e32 v[36:37], v[2:3]
	v_mov_b64_e32 v[38:39], v[2:3]
	v_mov_b64_e32 v[40:41], v[2:3]
	v_mov_b64_e32 v[42:43], v[2:3]
	v_mov_b64_e32 v[44:45], v[2:3]
	v_mov_b64_e32 v[46:47], v[2:3]
	v_mov_b64_e32 v[48:49], v[2:3]
	v_mov_b64_e32 v[50:51], v[2:3]
	v_mov_b64_e32 v[52:53], v[2:3]
	v_mov_b64_e32 v[54:55], v[2:3]
	v_mov_b64_e32 v[56:57], v[2:3]
	v_mov_b64_e32 v[58:59], v[2:3]
	v_mov_b64_e32 v[60:61], v[2:3]
	v_mov_b64_e32 v[62:63], v[2:3]
	v_mov_b64_e32 v[64:65], v[2:3]
	v_mov_b64_e32 v[66:67], v[2:3]
	v_mov_b64_e32 v[68:69], v[2:3]
	v_mov_b64_e32 v[70:71], v[2:3]
	v_mov_b64_e32 v[72:73], v[2:3]
	v_mov_b64_e32 v[74:75], v[2:3]
	v_mov_b64_e32 v[76:77], v[2:3]
	v_mov_b64_e32 v[78:79], v[2:3]
	v_mov_b64_e32 v[80:81], v[2:3]
	v_mov_b64_e32 v[82:83], v[2:3]
	v_mov_b64_e32 v[84:85], v[2:3]
	v_mov_b64_e32 v[86:87], v[2:3]
	v_mov_b64_e32 v[88:89], v[2:3]
	v_mov_b64_e32 v[90:91], v[2:3]
	v_mov_b64_e32 v[92:93], v[2:3]
	v_mov_b64_e32 v[94:95], v[2:3]
	v_mov_b64_e32 v[96:97], v[2:3]
	v_mov_b64_e32 v[98:99], v[2:3]
	v_mov_b64_e32 v[100:101], v[2:3]
	v_mov_b64_e32 v[102:103], v[2:3]
	v_mov_b64_e32 v[104:105], v[2:3]
	v_mov_b64_e32 v[106:107], v[2:3]
	v_mov_b64_e32 v[108:109], v[2:3]
	v_mov_b64_e32 v[110:111], v[2:3]
	v_mov_b64_e32 v[112:113], v[2:3]
	v_mov_b64_e32 v[114:115], v[2:3]
	v_mov_b64_e32 v[116:117], v[2:3]
	v_mov_b64_e32 v[118:119], v[2:3]
	v_mov_b64_e32 v[120:121], v[2:3]
	v_mov_b64_e32 v[122:123], v[2:3]
	v_mov_b64_e32 v[124:125], v[2:3]
	v_mov_b64_e32 v[126:127], v[2:3]
	v_mov_b64_e32 v[128:129], v[2:3]
